# adds: P1 K-loop back-edge pointer bumps moved ahead of the final barrier (loop-edge edit)
# baseline (speedup 1.0000x reference)
; #define PG8_STAGE(bufoff, gbase, voff) do { _Pragma("unroll") for (int _i = 0; _i < 2; ++_i) \
;         __builtin_amdgcn_global_load_lds((const unsigned*)((const char*)(gbase) + (voff)[_i]), (PG8_LAS unsigned*)(lds + (bufoff) + ldsw + _i * 8192), 16, 0, 0); } while (0)
; #define PG8_LDA(dst, b, h) do { _Pragma("unroll") for (int m = 0; m < 4; ++m) _Pragma("unroll") for (int k = 0; k < 2; ++k) dst[m][k] = *(const PG8_LAS bf16x8*)(lds + PG8_SA(b, h) + aoff + m * 2048 + k * 1024); } while (0)
; #define PG8_LDB(dst, b, h) do { _Pragma("unroll") for (int n = 0; n < 2; ++n) _Pragma("unroll") for (int k = 0; k < 2; ++k) dst[n][k] = *(const PG8_LAS bf16x8*)(lds + PG8_SB(b, h) + boff + n * 2048 + k * 1024); } while (0)
; #define PG8_MMA(ai, bj, At, Bt) do { __builtin_amdgcn_s_setprio(1); _Pragma("unroll") for (int m = 0; m < 4; ++m) _Pragma("unroll") for (int n = 0; n < 2; ++n) _Pragma("unroll") for (int k = 0; k < 2; ++k) \
;         acc[ai][bj][m][n] = __builtin_amdgcn_mfma_f32_16x16x32_bf16(Bt[n][k], At[m][k], acc[ai][bj][m][n], 0, 0, 0); __builtin_amdgcn_s_setprio(0); } while (0)
; #define PG8_WAIT_V(n) asm volatile("s_waitcnt vmcnt(" #n ")" ::: "memory")
; #define PG8_WAIT_L(n) asm volatile("s_waitcnt lgkmcnt(" #n ")" ::: "memory")
; #define PG8_BAR __builtin_amdgcn_s_barrier()
; #define PG8_SCHED __builtin_amdgcn_sched_barrier(0)
; template <class Epi, class Sched, bool ALIGN_EPI = false, bool SP2 = false>
; __device__ __forceinline__ void gemm_phase(PG8_LAS unsigned char* lds, const Gemm g, const Sched& S, const Epi& E) {
;     ...
;             PG8_LDB(B0, 0, 0); PG8_LDB(B1, 0, 1); PG8_SCHED; PG8_LDA(At, 0, 0); PG8_STAGE(PG8_SA(1, 1), a1 + hstep, voffA);
;             PG8_WAIT_V(8); PG8_WAIT_L(0); PG8_BAR; PG8_MMA(0, 0, At, B0); PG8_MMA(0, 1, At, B1); PG8_BAR; PG8_SCHED;
;             PG8_LDA(At, 0, 1); PG8_STAGE(PG8_SB(0, 0), b2, voffB); PG8_STAGE(PG8_SB(0, 1), b2 + hstep, voffB); PG8_STAGE(PG8_SA(0, 0), a2, voffA);
;             PG8_WAIT_V(8); PG8_WAIT_L(0); PG8_BAR; PG8_MMA(1, 0, At, B0); PG8_MMA(1, 1, At, B1); PG8_BAR; PG8_SCHED;
;             PG8_LDB(B0, 1, 0); PG8_LDB(B1, 1, 1); PG8_SCHED; PG8_LDA(At, 1, 0); PG8_STAGE(PG8_SA(0, 1), a2 + hstep, voffA);
;             PG8_WAIT_V(8); PG8_WAIT_L(0); PG8_BAR; PG8_MMA(0, 0, At, B0); PG8_MMA(0, 1, At, B1); PG8_BAR; PG8_SCHED;
.Lpeel_p1:
	s_add_u32 s40, s22, 0xfffc0080
	s_addc_u32 s41, s23, -1
	s_add_i32 s55, 0, 0x10000
	s_cmp_eq_u32 s49, 12
	s_cselect_b32 s61, s5, s41
	s_cselect_b32 s60, s7, s40
	s_cselect_b32 s41, s34, s47
	s_cselect_b32 s40, s35, s45
	s_add_i32 s57, 0, 0x14000
	v_add_u32_e32 v90, s55, v233
	v_add_u32_e32 v110, s57, v233
	ds_read_b128 v[74:77], v90
	ds_read_b128 v[78:81], v90 offset:1024
	ds_read_b128 v[82:85], v90 offset:2048
	ds_read_b128 v[90:93], v90 offset:3072
	ds_read_b128 v[94:97], v110
	ds_read_b128 v[98:101], v110 offset:1024
	ds_read_b128 v[102:105], v110 offset:2048
	ds_read_b128 v[110:113], v110 offset:3072
	v_lshl_add_u64 v[216:217], s[22:23], 0, v[188:189]
	s_add_i32 m0, s66, 0xc000
	ds_read_b128 v[162:165], v234
	ds_read_b128 v[166:169], v234 offset:1024
	ds_read_b128 v[192:195], v234 offset:2048
	ds_read_b128 v[196:199], v234 offset:3072
	ds_read_b128 v[200:203], v234 offset:4096
	ds_read_b128 v[204:207], v234 offset:5120
	ds_read_b128 v[208:211], v234 offset:6144
	ds_read_b128 v[212:215], v234 offset:7168
	v_lshl_add_u64 v[216:217], s[22:23], 0, v[190:191]
	s_add_i32 m0, s66, 0xe000
	s_nop 0
	s_waitcnt lgkmcnt(0)
	s_barrier
	s_setprio 1
	s_waitcnt lgkmcnt(0)
	v_mfma_f32_16x16x32_bf16 v[158:161], v[74:77], v[162:165], v[158:161]
	v_mfma_f32_16x16x32_bf16 v[154:157], v[82:85], v[162:165], v[154:157]
	v_mfma_f32_16x16x32_bf16 v[142:145], v[74:77], v[192:195], v[142:145]
	v_mfma_f32_16x16x32_bf16 v[138:141], v[82:85], v[192:195], v[138:141]
	v_mfma_f32_16x16x32_bf16 v[126:129], v[74:77], v[200:203], v[126:129]
	v_mfma_f32_16x16x32_bf16 v[122:125], v[82:85], v[200:203], v[122:125]
	v_mfma_f32_16x16x32_bf16 v[106:109], v[74:77], v[208:211], v[106:109]
	v_mfma_f32_16x16x32_bf16 v[86:89], v[82:85], v[208:211], v[86:89]
	v_mfma_f32_16x16x32_bf16 v[158:161], v[78:81], v[166:169], v[158:161]
	v_mfma_f32_16x16x32_bf16 v[154:157], v[90:93], v[166:169], v[154:157]
	v_mfma_f32_16x16x32_bf16 v[142:145], v[78:81], v[196:199], v[142:145]
	v_mfma_f32_16x16x32_bf16 v[138:141], v[90:93], v[196:199], v[138:141]
	v_mfma_f32_16x16x32_bf16 v[126:129], v[78:81], v[204:207], v[126:129]
	v_mfma_f32_16x16x32_bf16 v[122:125], v[90:93], v[204:207], v[122:125]
	v_mfma_f32_16x16x32_bf16 v[106:109], v[78:81], v[212:215], v[106:109]
	v_mfma_f32_16x16x32_bf16 v[86:89], v[90:93], v[212:215], v[86:89]
	s_setprio 0
	s_setprio 1
	v_mfma_f32_16x16x32_bf16 v[150:153], v[94:97], v[162:165], v[150:153]
	v_mfma_f32_16x16x32_bf16 v[146:149], v[102:105], v[162:165], v[146:149]
	v_mfma_f32_16x16x32_bf16 v[134:137], v[94:97], v[192:195], v[134:137]
	v_mfma_f32_16x16x32_bf16 v[130:133], v[102:105], v[192:195], v[130:133]
	v_mfma_f32_16x16x32_bf16 v[118:121], v[94:97], v[200:203], v[118:121]
	v_mfma_f32_16x16x32_bf16 v[114:117], v[102:105], v[200:203], v[114:117]
	v_mfma_f32_16x16x32_bf16 v[70:73], v[94:97], v[208:211], v[70:73]
	v_mfma_f32_16x16x32_bf16 v[66:69], v[102:105], v[208:211], v[66:69]
	v_mfma_f32_16x16x32_bf16 v[150:153], v[98:101], v[166:169], v[150:153]
	v_mfma_f32_16x16x32_bf16 v[146:149], v[110:113], v[166:169], v[146:149]
	v_mfma_f32_16x16x32_bf16 v[134:137], v[98:101], v[196:199], v[134:137]
	v_mfma_f32_16x16x32_bf16 v[130:133], v[110:113], v[196:199], v[130:133]
	v_mfma_f32_16x16x32_bf16 v[118:121], v[98:101], v[204:207], v[118:121]
	v_mfma_f32_16x16x32_bf16 v[114:117], v[110:113], v[204:207], v[114:117]
	v_mfma_f32_16x16x32_bf16 v[70:73], v[98:101], v[212:215], v[70:73]
	v_mfma_f32_16x16x32_bf16 v[66:69], v[110:113], v[212:215], v[66:69]
	s_setprio 0
	s_barrier
	s_add_i32 s55, s55, s65
	v_lshl_add_u64 v[216:217], s[40:41], 0, v[0:1]
	s_mov_b32 m0, s55
	ds_read_b128 v[162:165], v234 offset:16384
	ds_read_b128 v[166:169], v234 offset:17408
	ds_read_b128 v[192:195], v234 offset:18432
	ds_read_b128 v[196:199], v234 offset:19456
	ds_read_b128 v[200:203], v234 offset:20480
	ds_read_b128 v[204:207], v234 offset:21504
	ds_read_b128 v[208:211], v234 offset:22528
	ds_read_b128 v[212:215], v234 offset:23552
	global_load_lds_dwordx4 v[216:217], off
	s_add_i32 m0, s55, 0x2000
	s_add_u32 s62, s40, 0x40000
	v_lshl_add_u64 v[218:219], s[40:41], 0, v[186:187]
	s_addc_u32 s63, s41, 0
	s_add_i32 s55, s57, s65
	global_load_lds_dwordx4 v[218:219], off
	v_lshl_add_u64 v[236:237], s[62:63], 0, v[0:1]
	s_mov_b32 m0, s55
	v_lshl_add_u64 v[238:239], s[60:61], 0, v[184:185]
	global_load_lds_dwordx4 v[236:237], off
	v_lshl_add_u64 v[236:237], s[62:63], 0, v[186:187]
	s_add_i32 m0, s55, 0x2000
	s_nop 0
	global_load_lds_dwordx4 v[236:237], off
	v_lshl_add_u64 v[236:237], s[60:61], 0, v[182:183]
	s_mov_b32 m0, s66
	s_nop 0
	global_load_lds_dwordx4 v[236:237], off
	s_mov_b32 m0, s67
	s_nop 0
	global_load_lds_dwordx4 v[238:239], off
	s_waitcnt lgkmcnt(0)
	s_barrier
; #define PG8_STAGE(bufoff, gbase, voff) do { _Pragma("unroll") for (int _i = 0; _i < 2; ++_i) \
;         __builtin_amdgcn_global_load_lds((const unsigned*)((const char*)(gbase) + (voff)[_i]), (PG8_LAS unsigned*)(lds + (bufoff) + ldsw + _i * 8192), 16, 0, 0); } while (0)
; #define PG8_LDA(dst, b, h) do { _Pragma("unroll") for (int m = 0; m < 4; ++m) _Pragma("unroll") for (int k = 0; k < 2; ++k) dst[m][k] = *(const PG8_LAS bf16x8*)(lds + PG8_SA(b, h) + aoff + m * 2048 + k * 1024); } while (0)
; #define PG8_LDB(dst, b, h) do { _Pragma("unroll") for (int n = 0; n < 2; ++n) _Pragma("unroll") for (int k = 0; k < 2; ++k) dst[n][k] = *(const PG8_LAS bf16x8*)(lds + PG8_SB(b, h) + boff + n * 2048 + k * 1024); } while (0)
; #define PG8_MMA(ai, bj, At, Bt) do { __builtin_amdgcn_s_setprio(1); _Pragma("unroll") for (int m = 0; m < 4; ++m) _Pragma("unroll") for (int n = 0; n < 2; ++n) _Pragma("unroll") for (int k = 0; k < 2; ++k) \
;         acc[ai][bj][m][n] = __builtin_amdgcn_mfma_f32_16x16x32_bf16(Bt[n][k], At[m][k], acc[ai][bj][m][n], 0, 0, 0); __builtin_amdgcn_s_setprio(0); } while (0)
; #define PG8_WAIT_V(n) asm volatile("s_waitcnt vmcnt(" #n ")" ::: "memory")
; #define PG8_WAIT_L(n) asm volatile("s_waitcnt lgkmcnt(" #n ")" ::: "memory")
; #define PG8_BAR __builtin_amdgcn_s_barrier()
; #define PG8_SCHED __builtin_amdgcn_sched_barrier(0)
; template <class Epi, class Sched, bool ALIGN_EPI = false, bool SP2 = false>
; __device__ __forceinline__ void gemm_phase(PG8_LAS unsigned char* lds, const Gemm g, const Sched& S, const Epi& E) {
;     ...
;             PG8_WAIT_V(8); PG8_WAIT_L(0); PG8_BAR; PG8_MMA(1, 0, At, B0); PG8_MMA(1, 1, At, B1); PG8_BAR; PG8_SCHED;
;             PG8_LDB(B0, 1, 0); PG8_LDB(B1, 1, 1); PG8_SCHED; PG8_LDA(At, 1, 0); PG8_STAGE(PG8_SA(0, 1), a2 + hstep, voffA);
;             PG8_WAIT_V(8); PG8_WAIT_L(0); PG8_BAR; PG8_MMA(0, 0, At, B0); PG8_MMA(0, 1, At, B1); PG8_BAR; PG8_SCHED;
	s_setprio 1
	s_waitcnt lgkmcnt(0)
	v_mfma_f32_16x16x32_bf16 v[62:65], v[74:77], v[162:165], v[62:65]
	v_mfma_f32_16x16x32_bf16 v[58:61], v[82:85], v[162:165], v[58:61]
	v_mfma_f32_16x16x32_bf16 v[46:49], v[74:77], v[192:195], v[46:49]
	v_mfma_f32_16x16x32_bf16 v[42:45], v[82:85], v[192:195], v[42:45]
	v_mfma_f32_16x16x32_bf16 v[30:33], v[74:77], v[200:203], v[30:33]
	v_mfma_f32_16x16x32_bf16 v[26:29], v[82:85], v[200:203], v[26:29]
	v_mfma_f32_16x16x32_bf16 v[14:17], v[74:77], v[208:211], v[14:17]
	v_mfma_f32_16x16x32_bf16 v[10:13], v[82:85], v[208:211], v[10:13]
	v_mfma_f32_16x16x32_bf16 v[62:65], v[78:81], v[166:169], v[62:65]
	v_mfma_f32_16x16x32_bf16 v[58:61], v[90:93], v[166:169], v[58:61]
	v_mfma_f32_16x16x32_bf16 v[46:49], v[78:81], v[196:199], v[46:49]
	v_mfma_f32_16x16x32_bf16 v[42:45], v[90:93], v[196:199], v[42:45]
	v_mfma_f32_16x16x32_bf16 v[30:33], v[78:81], v[204:207], v[30:33]
	v_mfma_f32_16x16x32_bf16 v[26:29], v[90:93], v[204:207], v[26:29]
	v_mfma_f32_16x16x32_bf16 v[14:17], v[78:81], v[212:215], v[14:17]
	v_mfma_f32_16x16x32_bf16 v[10:13], v[90:93], v[212:215], v[10:13]
	s_setprio 0
	s_setprio 1
	v_mfma_f32_16x16x32_bf16 v[54:57], v[94:97], v[162:165], v[54:57]
	v_mfma_f32_16x16x32_bf16 v[50:53], v[102:105], v[162:165], v[50:53]
	v_mfma_f32_16x16x32_bf16 v[38:41], v[94:97], v[192:195], v[38:41]
	v_mfma_f32_16x16x32_bf16 v[34:37], v[102:105], v[192:195], v[34:37]
	v_mfma_f32_16x16x32_bf16 v[22:25], v[94:97], v[200:203], v[22:25]
	v_mfma_f32_16x16x32_bf16 v[18:21], v[102:105], v[200:203], v[18:21]
	v_mfma_f32_16x16x32_bf16 v[6:9], v[94:97], v[208:211], v[6:9]
	v_mfma_f32_16x16x32_bf16 v[2:5], v[102:105], v[208:211], v[2:5]
	v_mfma_f32_16x16x32_bf16 v[54:57], v[98:101], v[166:169], v[54:57]
	v_mfma_f32_16x16x32_bf16 v[50:53], v[110:113], v[166:169], v[50:53]
	v_mfma_f32_16x16x32_bf16 v[38:41], v[98:101], v[196:199], v[38:41]
	v_mfma_f32_16x16x32_bf16 v[34:37], v[110:113], v[196:199], v[34:37]
	v_mfma_f32_16x16x32_bf16 v[22:25], v[98:101], v[204:207], v[22:25]
	v_mfma_f32_16x16x32_bf16 v[18:21], v[110:113], v[204:207], v[18:21]
	v_mfma_f32_16x16x32_bf16 v[6:9], v[98:101], v[212:215], v[6:9]
	v_mfma_f32_16x16x32_bf16 v[2:5], v[110:113], v[212:215], v[2:5]
	s_setprio 0
	s_barrier
	s_add_i32 s55, 0, 0x18000
	s_add_i32 s57, 0, 0x1c000
	v_add_u32_e32 v90, s55, v233
	v_add_u32_e32 v110, s57, v233
	ds_read_b128 v[74:77], v90
	ds_read_b128 v[78:81], v90 offset:1024
	ds_read_b128 v[82:85], v90 offset:2048
	ds_read_b128 v[90:93], v90 offset:3072
	ds_read_b128 v[94:97], v110
	ds_read_b128 v[98:101], v110 offset:1024
	ds_read_b128 v[102:105], v110 offset:2048
	ds_read_b128 v[110:113], v110 offset:3072
	s_add_u32 s60, s60, 0x40000
	s_addc_u32 s61, s61, 0
	s_mov_b32 m0, s70
	v_lshl_add_u64 v[240:241], s[60:61], 0, v[182:183]
	ds_read_b128 v[162:165], v234 offset:32768
	ds_read_b128 v[166:169], v234 offset:33792
	ds_read_b128 v[192:195], v234 offset:34816
	ds_read_b128 v[196:199], v234 offset:35840
	ds_read_b128 v[200:203], v234 offset:36864
	ds_read_b128 v[204:207], v234 offset:37888
	ds_read_b128 v[208:211], v234 offset:38912
	ds_read_b128 v[212:215], v234 offset:39936
	global_load_lds_dwordx4 v[240:241], off
	v_lshl_add_u64 v[240:241], s[60:61], 0, v[184:185]
	s_mov_b32 m0, s71
	s_nop 0
	global_load_lds_dwordx4 v[240:241], off
	s_waitcnt lgkmcnt(0)
	s_barrier
	s_setprio 1
	s_waitcnt lgkmcnt(0)
	v_mfma_f32_16x16x32_bf16 v[158:161], v[74:77], v[162:165], v[158:161]
	v_mfma_f32_16x16x32_bf16 v[154:157], v[82:85], v[162:165], v[154:157]
	v_mfma_f32_16x16x32_bf16 v[142:145], v[74:77], v[192:195], v[142:145]
	v_mfma_f32_16x16x32_bf16 v[138:141], v[82:85], v[192:195], v[138:141]
	v_mfma_f32_16x16x32_bf16 v[126:129], v[74:77], v[200:203], v[126:129]
	v_mfma_f32_16x16x32_bf16 v[122:125], v[82:85], v[200:203], v[122:125]
	v_mfma_f32_16x16x32_bf16 v[106:109], v[74:77], v[208:211], v[106:109]
	v_mfma_f32_16x16x32_bf16 v[86:89], v[82:85], v[208:211], v[86:89]
	v_mfma_f32_16x16x32_bf16 v[158:161], v[78:81], v[166:169], v[158:161]
	v_mfma_f32_16x16x32_bf16 v[154:157], v[90:93], v[166:169], v[154:157]
	v_mfma_f32_16x16x32_bf16 v[142:145], v[78:81], v[196:199], v[142:145]
	v_mfma_f32_16x16x32_bf16 v[138:141], v[90:93], v[196:199], v[138:141]
	v_mfma_f32_16x16x32_bf16 v[126:129], v[78:81], v[204:207], v[126:129]
	v_mfma_f32_16x16x32_bf16 v[122:125], v[90:93], v[204:207], v[122:125]
	v_mfma_f32_16x16x32_bf16 v[106:109], v[78:81], v[212:215], v[106:109]
	v_mfma_f32_16x16x32_bf16 v[86:89], v[90:93], v[212:215], v[86:89]
	s_setprio 0
	s_setprio 1
	v_mfma_f32_16x16x32_bf16 v[150:153], v[94:97], v[162:165], v[150:153]
	v_mfma_f32_16x16x32_bf16 v[146:149], v[102:105], v[162:165], v[146:149]
	v_mfma_f32_16x16x32_bf16 v[134:137], v[94:97], v[192:195], v[134:137]
	v_mfma_f32_16x16x32_bf16 v[130:133], v[102:105], v[192:195], v[130:133]
	v_mfma_f32_16x16x32_bf16 v[118:121], v[94:97], v[200:203], v[118:121]
	v_mfma_f32_16x16x32_bf16 v[114:117], v[102:105], v[200:203], v[114:117]
	v_mfma_f32_16x16x32_bf16 v[70:73], v[94:97], v[208:211], v[70:73]
	v_mfma_f32_16x16x32_bf16 v[66:69], v[102:105], v[208:211], v[66:69]
	v_mfma_f32_16x16x32_bf16 v[150:153], v[98:101], v[166:169], v[150:153]
	v_mfma_f32_16x16x32_bf16 v[146:149], v[110:113], v[166:169], v[146:149]
	v_mfma_f32_16x16x32_bf16 v[134:137], v[98:101], v[196:199], v[134:137]
	v_mfma_f32_16x16x32_bf16 v[130:133], v[110:113], v[196:199], v[130:133]
	v_mfma_f32_16x16x32_bf16 v[118:121], v[98:101], v[204:207], v[118:121]
	v_mfma_f32_16x16x32_bf16 v[114:117], v[110:113], v[204:207], v[114:117]
	v_mfma_f32_16x16x32_bf16 v[70:73], v[98:101], v[212:215], v[70:73]
	v_mfma_f32_16x16x32_bf16 v[66:69], v[110:113], v[212:215], v[66:69]
	s_setprio 0
	s_barrier
; #define PG8_STAGE(bufoff, gbase, voff) do { _Pragma("unroll") for (int _i = 0; _i < 2; ++_i) \
;         __builtin_amdgcn_global_load_lds((const unsigned*)((const char*)(gbase) + (voff)[_i]), (PG8_LAS unsigned*)(lds + (bufoff) + ldsw + _i * 8192), 16, 0, 0); } while (0)
; #define PG8_LDA(dst, b, h) do { _Pragma("unroll") for (int m = 0; m < 4; ++m) _Pragma("unroll") for (int k = 0; k < 2; ++k) dst[m][k] = *(const PG8_LAS bf16x8*)(lds + PG8_SA(b, h) + aoff + m * 2048 + k * 1024); } while (0)
; #define PG8_LDB(dst, b, h) do { _Pragma("unroll") for (int n = 0; n < 2; ++n) _Pragma("unroll") for (int k = 0; k < 2; ++k) dst[n][k] = *(const PG8_LAS bf16x8*)(lds + PG8_SB(b, h) + boff + n * 2048 + k * 1024); } while (0)
; template <class Epi, class Sched, bool ALIGN_EPI = false, bool SP2 = false>
; __device__ __forceinline__ void gemm_phase(PG8_LAS unsigned char* lds, const Gemm g, const Sched& S, const Epi& E) {
;     ...
;         for (int t = 0; t < nt; t += 2) {
;             const bool last = (t == nt - 2);
;             const char* a1 = cA + (size_t)(t + 1) * kstep;
;             const char* a2 = last ? nA : cA + (size_t)(t + 2) * kstep; const char* b2 = last ? nB : cB + (size_t)(t + 2) * kstep;
;             const char* a3 = a2 + kstep; const char* b3 = b2 + kstep;
;             if (last && has_next) S.a_ready(nxt);
;             if constexpr (SP2) {
;             PG8_LDB(B0, 0, 0); PG8_LDB(B1, 0, 1); PG8_SCHED; PG8_LDA(At, 0, 0); PG8_STAGE(PG8_SA(1, 1), a1 + hstep, voffA);
;             PG8_WAIT_V(8); PG8_WAIT_L(0); PG8_BAR; PG8_MMA(0, 0, At, B0); PG8_MMA(0, 1, At, B1); PG8_BAR; PG8_SCHED;
;             PG8_LDA(At, 0, 1); PG8_STAGE(PG8_SB(0, 0), b2, voffB); PG8_STAGE(PG8_SB(0, 1), b2 + hstep, voffB); PG8_STAGE(PG8_SA(0, 0), a2, voffA);
;             PG8_WAIT_V(8); PG8_WAIT_L(0); PG8_BAR; PG8_MMA(1, 0, At, B0); PG8_MMA(1, 1, At, B1); PG8_BAR; PG8_SCHED;
;             PG8_LDB(B0, 1, 0); PG8_LDB(B1, 1, 1); PG8_SCHED; PG8_LDA(At, 1, 0); PG8_STAGE(PG8_SA(0, 1), a2 + hstep, voffA);
;             PG8_WAIT_V(8); PG8_WAIT_L(0); PG8_BAR; PG8_MMA(0, 0, At, B0); PG8_MMA(0, 1, At, B1); PG8_BAR; PG8_SCHED;
;             PG8_LDA(At, 1, 1); PG8_STAGE(PG8_SB(1, 0), b3, voffB); PG8_STAGE(PG8_SB(1, 1), b3 + hstep, voffB); PG8_STAGE(PG8_SA(1, 0), a3, voffA);
;             PG8_WAIT_V(8); PG8_WAIT_L(0); PG8_BAR; PG8_MMA(1, 0, At, B0); PG8_MMA(1, 1, At, B1); PG8_BAR; PG8_SCHED;
	s_add_i32 s55, s55, s65
	v_lshl_add_u64 v[216:217], v[216:217], 0, s[36:37]
	s_mov_b32 m0, s55
	ds_read_b128 v[162:165], v234 offset:49152
	ds_read_b128 v[166:169], v234 offset:50176
	ds_read_b128 v[192:195], v234 offset:51200
	ds_read_b128 v[196:199], v234 offset:52224
	ds_read_b128 v[200:203], v234 offset:53248
	ds_read_b128 v[204:207], v234 offset:54272
	ds_read_b128 v[208:211], v234 offset:55296
	ds_read_b128 v[212:215], v234 offset:56320
	global_load_lds_dwordx4 v[216:217], off
	s_add_i32 m0, s55, 0x2000
	s_add_u32 s40, s40, 0x40080
	v_lshl_add_u64 v[216:217], v[218:219], 0, s[36:37]
	s_addc_u32 s41, s41, 0
	s_add_i32 s55, s57, s65
	global_load_lds_dwordx4 v[216:217], off
	v_lshl_add_u64 v[216:217], s[40:41], 0, v[0:1]
	s_mov_b32 m0, s55
	s_nop 0
	global_load_lds_dwordx4 v[216:217], off
	v_lshl_add_u64 v[216:217], s[40:41], 0, v[186:187]
	s_add_i32 m0, s55, 0x2000
	s_nop 0
	global_load_lds_dwordx4 v[216:217], off
	v_lshl_add_u64 v[216:217], v[236:237], 0, s[36:37]
	s_mov_b32 m0, s76
	s_nop 0
	global_load_lds_dwordx4 v[216:217], off
	v_lshl_add_u64 v[216:217], v[238:239], 0, s[36:37]
	s_mov_b32 m0, s77
	s_nop 0
	global_load_lds_dwordx4 v[216:217], off
	s_waitcnt vmcnt(8)
	s_waitcnt lgkmcnt(0)
	s_barrier
	s_setprio 1
	s_waitcnt lgkmcnt(0)
	v_mfma_f32_16x16x32_bf16 v[62:65], v[74:77], v[162:165], v[62:65]
	v_mfma_f32_16x16x32_bf16 v[58:61], v[82:85], v[162:165], v[58:61]
	v_mfma_f32_16x16x32_bf16 v[46:49], v[74:77], v[192:195], v[46:49]
	v_mfma_f32_16x16x32_bf16 v[42:45], v[82:85], v[192:195], v[42:45]
	v_mfma_f32_16x16x32_bf16 v[30:33], v[74:77], v[200:203], v[30:33]
	v_mfma_f32_16x16x32_bf16 v[26:29], v[82:85], v[200:203], v[26:29]
	v_mfma_f32_16x16x32_bf16 v[14:17], v[74:77], v[208:211], v[14:17]
	v_mfma_f32_16x16x32_bf16 v[10:13], v[82:85], v[208:211], v[10:13]
	v_mfma_f32_16x16x32_bf16 v[62:65], v[78:81], v[166:169], v[62:65]
	v_mfma_f32_16x16x32_bf16 v[58:61], v[90:93], v[166:169], v[58:61]
	v_mfma_f32_16x16x32_bf16 v[46:49], v[78:81], v[196:199], v[46:49]
	v_mfma_f32_16x16x32_bf16 v[42:45], v[90:93], v[196:199], v[42:45]
	v_mfma_f32_16x16x32_bf16 v[30:33], v[78:81], v[204:207], v[30:33]
	v_mfma_f32_16x16x32_bf16 v[26:29], v[90:93], v[204:207], v[26:29]
	v_mfma_f32_16x16x32_bf16 v[14:17], v[78:81], v[212:215], v[14:17]
	v_mfma_f32_16x16x32_bf16 v[10:13], v[90:93], v[212:215], v[10:13]
	s_setprio 0
	s_setprio 1
	v_mfma_f32_16x16x32_bf16 v[54:57], v[94:97], v[162:165], v[54:57]
	v_mfma_f32_16x16x32_bf16 v[50:53], v[102:105], v[162:165], v[50:53]
	v_mfma_f32_16x16x32_bf16 v[38:41], v[94:97], v[192:195], v[38:41]
	v_mfma_f32_16x16x32_bf16 v[34:37], v[102:105], v[192:195], v[34:37]
	v_mfma_f32_16x16x32_bf16 v[22:25], v[94:97], v[200:203], v[22:25]
	v_mfma_f32_16x16x32_bf16 v[18:21], v[102:105], v[200:203], v[18:21]
	v_mfma_f32_16x16x32_bf16 v[6:9], v[94:97], v[208:211], v[6:9]
	v_mfma_f32_16x16x32_bf16 v[2:5], v[102:105], v[208:211], v[2:5]
	v_mfma_f32_16x16x32_bf16 v[54:57], v[98:101], v[166:169], v[54:57]
	v_mfma_f32_16x16x32_bf16 v[50:53], v[110:113], v[166:169], v[50:53]
	v_mfma_f32_16x16x32_bf16 v[38:41], v[98:101], v[196:199], v[38:41]
	v_mfma_f32_16x16x32_bf16 v[34:37], v[110:113], v[196:199], v[34:37]
	v_mfma_f32_16x16x32_bf16 v[22:25], v[98:101], v[204:207], v[22:25]
	v_mfma_f32_16x16x32_bf16 v[18:21], v[110:113], v[204:207], v[18:21]
	v_mfma_f32_16x16x32_bf16 v[6:9], v[98:101], v[212:215], v[6:9]
	v_mfma_f32_16x16x32_bf16 v[2:5], v[110:113], v[212:215], v[2:5]
	s_setprio 0
	s_add_i32 s49, s49, 2
	s_add_u32 s22, s22, 0x100
	s_addc_u32 s23, s23, 0
	s_add_u32 s45, s45, 0x100
	s_addc_u32 s47, s47, 0
	s_barrier
	s_cmp_gt_u32 s49, 13
	s_cbranch_scc0 .LBB0_157
	s_branch .Lafter_157
.LBB0_157:
	s_add_u32 s40, s22, 0xfffc0080
	s_addc_u32 s41, s23, -1
	s_add_i32 s55, 0, 0x10000
	s_cmp_eq_u32 s49, 12
	s_cselect_b32 s61, s5, s41
	s_cselect_b32 s60, s7, s40
	s_cselect_b32 s41, s34, s47
	s_cselect_b32 s40, s35, s45
	s_add_i32 s57, 0, 0x14000
	v_add_u32_e32 v90, s55, v233
	v_add_u32_e32 v110, s57, v233
	ds_read_b128 v[74:77], v90
	ds_read_b128 v[78:81], v90 offset:1024
	ds_read_b128 v[82:85], v90 offset:2048
	ds_read_b128 v[90:93], v90 offset:3072
	ds_read_b128 v[94:97], v110
	ds_read_b128 v[98:101], v110 offset:1024
	ds_read_b128 v[102:105], v110 offset:2048
	ds_read_b128 v[110:113], v110 offset:3072
	v_lshl_add_u64 v[216:217], s[22:23], 0, v[188:189]
	s_add_i32 m0, s66, 0xc000
	ds_read_b128 v[162:165], v234
	ds_read_b128 v[166:169], v234 offset:1024
	ds_read_b128 v[192:195], v234 offset:2048
	ds_read_b128 v[196:199], v234 offset:3072
	ds_read_b128 v[200:203], v234 offset:4096
	ds_read_b128 v[204:207], v234 offset:5120
	ds_read_b128 v[208:211], v234 offset:6144
	ds_read_b128 v[212:215], v234 offset:7168
	global_load_lds_dwordx4 v[216:217], off
	v_lshl_add_u64 v[216:217], s[22:23], 0, v[190:191]
	s_add_i32 m0, s66, 0xe000
	s_nop 0
	global_load_lds_dwordx4 v[216:217], off
	s_waitcnt vmcnt(8)
	s_waitcnt lgkmcnt(0)
	s_barrier
; #define PG8_STAGE(bufoff, gbase, voff) do { _Pragma("unroll") for (int _i = 0; _i < 2; ++_i) \
;         __builtin_amdgcn_global_load_lds((const unsigned*)((const char*)(gbase) + (voff)[_i]), (PG8_LAS unsigned*)(lds + (bufoff) + ldsw + _i * 8192), 16, 0, 0); } while (0)
; #define PG8_LDA(dst, b, h) do { _Pragma("unroll") for (int m = 0; m < 4; ++m) _Pragma("unroll") for (int k = 0; k < 2; ++k) dst[m][k] = *(const PG8_LAS bf16x8*)(lds + PG8_SA(b, h) + aoff + m * 2048 + k * 1024); } while (0)
; #define PG8_LDB(dst, b, h) do { _Pragma("unroll") for (int n = 0; n < 2; ++n) _Pragma("unroll") for (int k = 0; k < 2; ++k) dst[n][k] = *(const PG8_LAS bf16x8*)(lds + PG8_SB(b, h) + boff + n * 2048 + k * 1024); } while (0)
; #define PG8_MMA(ai, bj, At, Bt) do { __builtin_amdgcn_s_setprio(1); _Pragma("unroll") for (int m = 0; m < 4; ++m) _Pragma("unroll") for (int n = 0; n < 2; ++n) _Pragma("unroll") for (int k = 0; k < 2; ++k) \
;         acc[ai][bj][m][n] = __builtin_amdgcn_mfma_f32_16x16x32_bf16(Bt[n][k], At[m][k], acc[ai][bj][m][n], 0, 0, 0); __builtin_amdgcn_s_setprio(0); } while (0)
; #define PG8_WAIT_V(n) asm volatile("s_waitcnt vmcnt(" #n ")" ::: "memory")
; #define PG8_WAIT_L(n) asm volatile("s_waitcnt lgkmcnt(" #n ")" ::: "memory")
; #define PG8_BAR __builtin_amdgcn_s_barrier()
; #define PG8_SCHED __builtin_amdgcn_sched_barrier(0)
; template <class Epi, class Sched, bool ALIGN_EPI = false, bool SP2 = false>
; __device__ __forceinline__ void gemm_phase(PG8_LAS unsigned char* lds, const Gemm g, const Sched& S, const Epi& E) {
;     ...
;             PG8_LDB(B0, 0, 0); PG8_LDB(B1, 0, 1); PG8_SCHED; PG8_LDA(At, 0, 0); PG8_STAGE(PG8_SA(1, 1), a1 + hstep, voffA);
;             PG8_WAIT_V(8); PG8_WAIT_L(0); PG8_BAR; PG8_MMA(0, 0, At, B0); PG8_MMA(0, 1, At, B1); PG8_BAR; PG8_SCHED;
;             PG8_LDA(At, 0, 1); PG8_STAGE(PG8_SB(0, 0), b2, voffB); PG8_STAGE(PG8_SB(0, 1), b2 + hstep, voffB); PG8_STAGE(PG8_SA(0, 0), a2, voffA);
;             PG8_WAIT_V(8); PG8_WAIT_L(0); PG8_BAR; PG8_MMA(1, 0, At, B0); PG8_MMA(1, 1, At, B1); PG8_BAR; PG8_SCHED;
	s_setprio 1
	s_waitcnt lgkmcnt(0)
	v_mfma_f32_16x16x32_bf16 v[158:161], v[74:77], v[162:165], v[158:161]
	v_mfma_f32_16x16x32_bf16 v[154:157], v[82:85], v[162:165], v[154:157]
	v_mfma_f32_16x16x32_bf16 v[142:145], v[74:77], v[192:195], v[142:145]
	v_mfma_f32_16x16x32_bf16 v[138:141], v[82:85], v[192:195], v[138:141]
	v_mfma_f32_16x16x32_bf16 v[126:129], v[74:77], v[200:203], v[126:129]
	v_mfma_f32_16x16x32_bf16 v[122:125], v[82:85], v[200:203], v[122:125]
	v_mfma_f32_16x16x32_bf16 v[106:109], v[74:77], v[208:211], v[106:109]
	v_mfma_f32_16x16x32_bf16 v[86:89], v[82:85], v[208:211], v[86:89]
	v_mfma_f32_16x16x32_bf16 v[158:161], v[78:81], v[166:169], v[158:161]
	v_mfma_f32_16x16x32_bf16 v[154:157], v[90:93], v[166:169], v[154:157]
	v_mfma_f32_16x16x32_bf16 v[142:145], v[78:81], v[196:199], v[142:145]
	v_mfma_f32_16x16x32_bf16 v[138:141], v[90:93], v[196:199], v[138:141]
	v_mfma_f32_16x16x32_bf16 v[126:129], v[78:81], v[204:207], v[126:129]
	v_mfma_f32_16x16x32_bf16 v[122:125], v[90:93], v[204:207], v[122:125]
	v_mfma_f32_16x16x32_bf16 v[106:109], v[78:81], v[212:215], v[106:109]
	v_mfma_f32_16x16x32_bf16 v[86:89], v[90:93], v[212:215], v[86:89]
	s_setprio 0
	s_setprio 1
	v_mfma_f32_16x16x32_bf16 v[150:153], v[94:97], v[162:165], v[150:153]
	v_mfma_f32_16x16x32_bf16 v[146:149], v[102:105], v[162:165], v[146:149]
	v_mfma_f32_16x16x32_bf16 v[134:137], v[94:97], v[192:195], v[134:137]
	v_mfma_f32_16x16x32_bf16 v[130:133], v[102:105], v[192:195], v[130:133]
	v_mfma_f32_16x16x32_bf16 v[118:121], v[94:97], v[200:203], v[118:121]
	v_mfma_f32_16x16x32_bf16 v[114:117], v[102:105], v[200:203], v[114:117]
	v_mfma_f32_16x16x32_bf16 v[70:73], v[94:97], v[208:211], v[70:73]
	v_mfma_f32_16x16x32_bf16 v[66:69], v[102:105], v[208:211], v[66:69]
	v_mfma_f32_16x16x32_bf16 v[150:153], v[98:101], v[166:169], v[150:153]
	v_mfma_f32_16x16x32_bf16 v[146:149], v[110:113], v[166:169], v[146:149]
	v_mfma_f32_16x16x32_bf16 v[134:137], v[98:101], v[196:199], v[134:137]
	v_mfma_f32_16x16x32_bf16 v[130:133], v[110:113], v[196:199], v[130:133]
	v_mfma_f32_16x16x32_bf16 v[118:121], v[98:101], v[204:207], v[118:121]
	v_mfma_f32_16x16x32_bf16 v[114:117], v[110:113], v[204:207], v[114:117]
	v_mfma_f32_16x16x32_bf16 v[70:73], v[98:101], v[212:215], v[70:73]
	v_mfma_f32_16x16x32_bf16 v[66:69], v[110:113], v[212:215], v[66:69]
	s_setprio 0
	s_barrier
	s_add_i32 s55, s55, s65
	v_lshl_add_u64 v[216:217], s[40:41], 0, v[0:1]
	s_mov_b32 m0, s55
	ds_read_b128 v[162:165], v234 offset:16384
	ds_read_b128 v[166:169], v234 offset:17408
	ds_read_b128 v[192:195], v234 offset:18432
	ds_read_b128 v[196:199], v234 offset:19456
	ds_read_b128 v[200:203], v234 offset:20480
	ds_read_b128 v[204:207], v234 offset:21504
	ds_read_b128 v[208:211], v234 offset:22528
	ds_read_b128 v[212:215], v234 offset:23552
	global_load_lds_dwordx4 v[216:217], off
	s_add_i32 m0, s55, 0x2000
	s_add_u32 s62, s40, 0x40000
	v_lshl_add_u64 v[218:219], s[40:41], 0, v[186:187]
	s_addc_u32 s63, s41, 0
	s_add_i32 s55, s57, s65
	global_load_lds_dwordx4 v[218:219], off
	v_lshl_add_u64 v[236:237], s[62:63], 0, v[0:1]
	s_mov_b32 m0, s55
	v_lshl_add_u64 v[238:239], s[60:61], 0, v[184:185]
	global_load_lds_dwordx4 v[236:237], off
	v_lshl_add_u64 v[236:237], s[62:63], 0, v[186:187]
	s_add_i32 m0, s55, 0x2000
	s_nop 0
	global_load_lds_dwordx4 v[236:237], off
	v_lshl_add_u64 v[236:237], s[60:61], 0, v[182:183]
	s_mov_b32 m0, s66
	s_nop 0
	global_load_lds_dwordx4 v[236:237], off
	s_mov_b32 m0, s67
	s_nop 0
	global_load_lds_dwordx4 v[238:239], off
	s_waitcnt vmcnt(8)
	s_waitcnt lgkmcnt(0)
	s_barrier
	s_setprio 1
	s_waitcnt lgkmcnt(0)
	v_mfma_f32_16x16x32_bf16 v[62:65], v[74:77], v[162:165], v[62:65]
	v_mfma_f32_16x16x32_bf16 v[58:61], v[82:85], v[162:165], v[58:61]
	v_mfma_f32_16x16x32_bf16 v[46:49], v[74:77], v[192:195], v[46:49]
	v_mfma_f32_16x16x32_bf16 v[42:45], v[82:85], v[192:195], v[42:45]
	v_mfma_f32_16x16x32_bf16 v[30:33], v[74:77], v[200:203], v[30:33]
	v_mfma_f32_16x16x32_bf16 v[26:29], v[82:85], v[200:203], v[26:29]
	v_mfma_f32_16x16x32_bf16 v[14:17], v[74:77], v[208:211], v[14:17]
	v_mfma_f32_16x16x32_bf16 v[10:13], v[82:85], v[208:211], v[10:13]
	v_mfma_f32_16x16x32_bf16 v[62:65], v[78:81], v[166:169], v[62:65]
	v_mfma_f32_16x16x32_bf16 v[58:61], v[90:93], v[166:169], v[58:61]
	v_mfma_f32_16x16x32_bf16 v[46:49], v[78:81], v[196:199], v[46:49]
	v_mfma_f32_16x16x32_bf16 v[42:45], v[90:93], v[196:199], v[42:45]
	v_mfma_f32_16x16x32_bf16 v[30:33], v[78:81], v[204:207], v[30:33]
	v_mfma_f32_16x16x32_bf16 v[26:29], v[90:93], v[204:207], v[26:29]
	v_mfma_f32_16x16x32_bf16 v[14:17], v[78:81], v[212:215], v[14:17]
	v_mfma_f32_16x16x32_bf16 v[10:13], v[90:93], v[212:215], v[10:13]
	s_setprio 0
	s_setprio 1
	v_mfma_f32_16x16x32_bf16 v[54:57], v[94:97], v[162:165], v[54:57]
	v_mfma_f32_16x16x32_bf16 v[50:53], v[102:105], v[162:165], v[50:53]
	v_mfma_f32_16x16x32_bf16 v[38:41], v[94:97], v[192:195], v[38:41]
	v_mfma_f32_16x16x32_bf16 v[34:37], v[102:105], v[192:195], v[34:37]
	v_mfma_f32_16x16x32_bf16 v[22:25], v[94:97], v[200:203], v[22:25]
	v_mfma_f32_16x16x32_bf16 v[18:21], v[102:105], v[200:203], v[18:21]
	v_mfma_f32_16x16x32_bf16 v[6:9], v[94:97], v[208:211], v[6:9]
	v_mfma_f32_16x16x32_bf16 v[2:5], v[102:105], v[208:211], v[2:5]
	v_mfma_f32_16x16x32_bf16 v[54:57], v[98:101], v[166:169], v[54:57]
	v_mfma_f32_16x16x32_bf16 v[50:53], v[110:113], v[166:169], v[50:53]
	v_mfma_f32_16x16x32_bf16 v[38:41], v[98:101], v[196:199], v[38:41]
	v_mfma_f32_16x16x32_bf16 v[34:37], v[110:113], v[196:199], v[34:37]
	v_mfma_f32_16x16x32_bf16 v[22:25], v[98:101], v[204:207], v[22:25]
	v_mfma_f32_16x16x32_bf16 v[18:21], v[110:113], v[204:207], v[18:21]
	v_mfma_f32_16x16x32_bf16 v[6:9], v[98:101], v[212:215], v[6:9]
	v_mfma_f32_16x16x32_bf16 v[2:5], v[110:113], v[212:215], v[2:5]
	s_setprio 0
	s_barrier
; #define PG8_STAGE(bufoff, gbase, voff) do { _Pragma("unroll") for (int _i = 0; _i < 2; ++_i) \
;         __builtin_amdgcn_global_load_lds((const unsigned*)((const char*)(gbase) + (voff)[_i]), (PG8_LAS unsigned*)(lds + (bufoff) + ldsw + _i * 8192), 16, 0, 0); } while (0)
; #define PG8_LDA(dst, b, h) do { _Pragma("unroll") for (int m = 0; m < 4; ++m) _Pragma("unroll") for (int k = 0; k < 2; ++k) dst[m][k] = *(const PG8_LAS bf16x8*)(lds + PG8_SA(b, h) + aoff + m * 2048 + k * 1024); } while (0)
; #define PG8_LDB(dst, b, h) do { _Pragma("unroll") for (int n = 0; n < 2; ++n) _Pragma("unroll") for (int k = 0; k < 2; ++k) dst[n][k] = *(const PG8_LAS bf16x8*)(lds + PG8_SB(b, h) + boff + n * 2048 + k * 1024); } while (0)
; #define PG8_MMA(ai, bj, At, Bt) do { __builtin_amdgcn_s_setprio(1); _Pragma("unroll") for (int m = 0; m < 4; ++m) _Pragma("unroll") for (int n = 0; n < 2; ++n) _Pragma("unroll") for (int k = 0; k < 2; ++k) \
;         acc[ai][bj][m][n] = __builtin_amdgcn_mfma_f32_16x16x32_bf16(Bt[n][k], At[m][k], acc[ai][bj][m][n], 0, 0, 0); __builtin_amdgcn_s_setprio(0); } while (0)
; #define PG8_WAIT_V(n) asm volatile("s_waitcnt vmcnt(" #n ")" ::: "memory")
; #define PG8_WAIT_L(n) asm volatile("s_waitcnt lgkmcnt(" #n ")" ::: "memory")
; #define PG8_BAR __builtin_amdgcn_s_barrier()
; #define PG8_SCHED __builtin_amdgcn_sched_barrier(0)
; template <class Epi, class Sched, bool ALIGN_EPI = false, bool SP2 = false>
; __device__ __forceinline__ void gemm_phase(PG8_LAS unsigned char* lds, const Gemm g, const Sched& S, const Epi& E) {
;     ...
;             PG8_LDB(B0, 1, 0); PG8_LDB(B1, 1, 1); PG8_SCHED; PG8_LDA(At, 1, 0); PG8_STAGE(PG8_SA(0, 1), a2 + hstep, voffA);
;             PG8_WAIT_V(8); PG8_WAIT_L(0); PG8_BAR; PG8_MMA(0, 0, At, B0); PG8_MMA(0, 1, At, B1); PG8_BAR; PG8_SCHED;
	s_add_i32 s55, 0, 0x18000
	s_add_i32 s57, 0, 0x1c000
	v_add_u32_e32 v90, s55, v233
	v_add_u32_e32 v110, s57, v233
	ds_read_b128 v[74:77], v90
	ds_read_b128 v[78:81], v90 offset:1024
	ds_read_b128 v[82:85], v90 offset:2048
	ds_read_b128 v[90:93], v90 offset:3072
	ds_read_b128 v[94:97], v110
	ds_read_b128 v[98:101], v110 offset:1024
	ds_read_b128 v[102:105], v110 offset:2048
	ds_read_b128 v[110:113], v110 offset:3072
	s_add_u32 s60, s60, 0x40000
	s_addc_u32 s61, s61, 0
	s_mov_b32 m0, s70
	v_lshl_add_u64 v[240:241], s[60:61], 0, v[182:183]
	ds_read_b128 v[162:165], v234 offset:32768
	ds_read_b128 v[166:169], v234 offset:33792
	ds_read_b128 v[192:195], v234 offset:34816
	ds_read_b128 v[196:199], v234 offset:35840
	ds_read_b128 v[200:203], v234 offset:36864
	ds_read_b128 v[204:207], v234 offset:37888
	ds_read_b128 v[208:211], v234 offset:38912
	ds_read_b128 v[212:215], v234 offset:39936
	global_load_lds_dwordx4 v[240:241], off
	v_lshl_add_u64 v[240:241], s[60:61], 0, v[184:185]
	s_mov_b32 m0, s71
	s_nop 0
	global_load_lds_dwordx4 v[240:241], off
	s_waitcnt vmcnt(8)
	s_waitcnt lgkmcnt(0)
	s_barrier
	s_setprio 1
	s_waitcnt lgkmcnt(0)
	v_mfma_f32_16x16x32_bf16 v[158:161], v[74:77], v[162:165], v[158:161]
	v_mfma_f32_16x16x32_bf16 v[154:157], v[82:85], v[162:165], v[154:157]
	v_mfma_f32_16x16x32_bf16 v[142:145], v[74:77], v[192:195], v[142:145]
	v_mfma_f32_16x16x32_bf16 v[138:141], v[82:85], v[192:195], v[138:141]
	v_mfma_f32_16x16x32_bf16 v[126:129], v[74:77], v[200:203], v[126:129]
	v_mfma_f32_16x16x32_bf16 v[122:125], v[82:85], v[200:203], v[122:125]
	v_mfma_f32_16x16x32_bf16 v[106:109], v[74:77], v[208:211], v[106:109]
	v_mfma_f32_16x16x32_bf16 v[86:89], v[82:85], v[208:211], v[86:89]
	v_mfma_f32_16x16x32_bf16 v[158:161], v[78:81], v[166:169], v[158:161]
	v_mfma_f32_16x16x32_bf16 v[154:157], v[90:93], v[166:169], v[154:157]
	v_mfma_f32_16x16x32_bf16 v[142:145], v[78:81], v[196:199], v[142:145]
	v_mfma_f32_16x16x32_bf16 v[138:141], v[90:93], v[196:199], v[138:141]
	v_mfma_f32_16x16x32_bf16 v[126:129], v[78:81], v[204:207], v[126:129]
	v_mfma_f32_16x16x32_bf16 v[122:125], v[90:93], v[204:207], v[122:125]
	v_mfma_f32_16x16x32_bf16 v[106:109], v[78:81], v[212:215], v[106:109]
	v_mfma_f32_16x16x32_bf16 v[86:89], v[90:93], v[212:215], v[86:89]
	s_setprio 0
	s_setprio 1
	v_mfma_f32_16x16x32_bf16 v[150:153], v[94:97], v[162:165], v[150:153]
	v_mfma_f32_16x16x32_bf16 v[146:149], v[102:105], v[162:165], v[146:149]
	v_mfma_f32_16x16x32_bf16 v[134:137], v[94:97], v[192:195], v[134:137]
	v_mfma_f32_16x16x32_bf16 v[130:133], v[102:105], v[192:195], v[130:133]
	v_mfma_f32_16x16x32_bf16 v[118:121], v[94:97], v[200:203], v[118:121]
	v_mfma_f32_16x16x32_bf16 v[114:117], v[102:105], v[200:203], v[114:117]
	v_mfma_f32_16x16x32_bf16 v[70:73], v[94:97], v[208:211], v[70:73]
	v_mfma_f32_16x16x32_bf16 v[66:69], v[102:105], v[208:211], v[66:69]
	v_mfma_f32_16x16x32_bf16 v[150:153], v[98:101], v[166:169], v[150:153]
	v_mfma_f32_16x16x32_bf16 v[146:149], v[110:113], v[166:169], v[146:149]
	v_mfma_f32_16x16x32_bf16 v[134:137], v[98:101], v[196:199], v[134:137]
	v_mfma_f32_16x16x32_bf16 v[130:133], v[110:113], v[196:199], v[130:133]
	v_mfma_f32_16x16x32_bf16 v[118:121], v[98:101], v[204:207], v[118:121]
	v_mfma_f32_16x16x32_bf16 v[114:117], v[110:113], v[204:207], v[114:117]
	v_mfma_f32_16x16x32_bf16 v[70:73], v[98:101], v[212:215], v[70:73]
	v_mfma_f32_16x16x32_bf16 v[66:69], v[110:113], v[212:215], v[66:69]
	s_setprio 0
	s_barrier
; #define PG8_STAGE(bufoff, gbase, voff) do { _Pragma("unroll") for (int _i = 0; _i < 2; ++_i) \
;         __builtin_amdgcn_global_load_lds((const unsigned*)((const char*)(gbase) + (voff)[_i]), (PG8_LAS unsigned*)(lds + (bufoff) + ldsw + _i * 8192), 16, 0, 0); } while (0)
; #define PG8_LDA(dst, b, h) do { _Pragma("unroll") for (int m = 0; m < 4; ++m) _Pragma("unroll") for (int k = 0; k < 2; ++k) dst[m][k] = *(const PG8_LAS bf16x8*)(lds + PG8_SA(b, h) + aoff + m * 2048 + k * 1024); } while (0)
; #define PG8_LDB(dst, b, h) do { _Pragma("unroll") for (int n = 0; n < 2; ++n) _Pragma("unroll") for (int k = 0; k < 2; ++k) dst[n][k] = *(const PG8_LAS bf16x8*)(lds + PG8_SB(b, h) + boff + n * 2048 + k * 1024); } while (0)
; template <class Epi, class Sched, bool ALIGN_EPI = false, bool SP2 = false>
; __device__ __forceinline__ void gemm_phase(PG8_LAS unsigned char* lds, const Gemm g, const Sched& S, const Epi& E) {
;     ...
;         for (int t = 0; t < nt; t += 2) {
;             const bool last = (t == nt - 2);
;             const char* a1 = cA + (size_t)(t + 1) * kstep;
;             const char* a2 = last ? nA : cA + (size_t)(t + 2) * kstep; const char* b2 = last ? nB : cB + (size_t)(t + 2) * kstep;
;             const char* a3 = a2 + kstep; const char* b3 = b2 + kstep;
;             if (last && has_next) S.a_ready(nxt);
;             if constexpr (SP2) {
;             PG8_LDB(B0, 0, 0); PG8_LDB(B1, 0, 1); PG8_SCHED; PG8_LDA(At, 0, 0); PG8_STAGE(PG8_SA(1, 1), a1 + hstep, voffA);
;             PG8_WAIT_V(8); PG8_WAIT_L(0); PG8_BAR; PG8_MMA(0, 0, At, B0); PG8_MMA(0, 1, At, B1); PG8_BAR; PG8_SCHED;
;             PG8_LDA(At, 0, 1); PG8_STAGE(PG8_SB(0, 0), b2, voffB); PG8_STAGE(PG8_SB(0, 1), b2 + hstep, voffB); PG8_STAGE(PG8_SA(0, 0), a2, voffA);
;             PG8_WAIT_V(8); PG8_WAIT_L(0); PG8_BAR; PG8_MMA(1, 0, At, B0); PG8_MMA(1, 1, At, B1); PG8_BAR; PG8_SCHED;
;             PG8_LDB(B0, 1, 0); PG8_LDB(B1, 1, 1); PG8_SCHED; PG8_LDA(At, 1, 0); PG8_STAGE(PG8_SA(0, 1), a2 + hstep, voffA);
;             PG8_WAIT_V(8); PG8_WAIT_L(0); PG8_BAR; PG8_MMA(0, 0, At, B0); PG8_MMA(0, 1, At, B1); PG8_BAR; PG8_SCHED;
;             PG8_LDA(At, 1, 1); PG8_STAGE(PG8_SB(1, 0), b3, voffB); PG8_STAGE(PG8_SB(1, 1), b3 + hstep, voffB); PG8_STAGE(PG8_SA(1, 0), a3, voffA);
;             PG8_WAIT_V(8); PG8_WAIT_L(0); PG8_BAR; PG8_MMA(1, 0, At, B0); PG8_MMA(1, 1, At, B1); PG8_BAR; PG8_SCHED;
	s_add_i32 s55, s55, s65
	v_lshl_add_u64 v[216:217], v[216:217], 0, s[36:37]
	s_mov_b32 m0, s55
	ds_read_b128 v[162:165], v234 offset:49152
	ds_read_b128 v[166:169], v234 offset:50176
	ds_read_b128 v[192:195], v234 offset:51200
	ds_read_b128 v[196:199], v234 offset:52224
	ds_read_b128 v[200:203], v234 offset:53248
	ds_read_b128 v[204:207], v234 offset:54272
	ds_read_b128 v[208:211], v234 offset:55296
	ds_read_b128 v[212:215], v234 offset:56320
	global_load_lds_dwordx4 v[216:217], off
	s_add_i32 m0, s55, 0x2000
	s_add_u32 s40, s40, 0x40080
	v_lshl_add_u64 v[216:217], v[218:219], 0, s[36:37]
	s_addc_u32 s41, s41, 0
	s_add_i32 s55, s57, s65
	global_load_lds_dwordx4 v[216:217], off
	v_lshl_add_u64 v[216:217], s[40:41], 0, v[0:1]
	s_mov_b32 m0, s55
	s_nop 0
	global_load_lds_dwordx4 v[216:217], off
	v_lshl_add_u64 v[216:217], s[40:41], 0, v[186:187]
	s_add_i32 m0, s55, 0x2000
	s_nop 0
	global_load_lds_dwordx4 v[216:217], off
	v_lshl_add_u64 v[216:217], v[236:237], 0, s[36:37]
	s_mov_b32 m0, s76
	s_nop 0
	global_load_lds_dwordx4 v[216:217], off
	v_lshl_add_u64 v[216:217], v[238:239], 0, s[36:37]
	s_mov_b32 m0, s77
	s_nop 0
	global_load_lds_dwordx4 v[216:217], off
	s_waitcnt vmcnt(8)
	s_waitcnt lgkmcnt(0)
	s_barrier
	s_setprio 1
	s_waitcnt lgkmcnt(0)
	v_mfma_f32_16x16x32_bf16 v[62:65], v[74:77], v[162:165], v[62:65]
	v_mfma_f32_16x16x32_bf16 v[58:61], v[82:85], v[162:165], v[58:61]
	v_mfma_f32_16x16x32_bf16 v[46:49], v[74:77], v[192:195], v[46:49]
	v_mfma_f32_16x16x32_bf16 v[42:45], v[82:85], v[192:195], v[42:45]
	v_mfma_f32_16x16x32_bf16 v[30:33], v[74:77], v[200:203], v[30:33]
	v_mfma_f32_16x16x32_bf16 v[26:29], v[82:85], v[200:203], v[26:29]
	v_mfma_f32_16x16x32_bf16 v[14:17], v[74:77], v[208:211], v[14:17]
	v_mfma_f32_16x16x32_bf16 v[10:13], v[82:85], v[208:211], v[10:13]
	v_mfma_f32_16x16x32_bf16 v[62:65], v[78:81], v[166:169], v[62:65]
	v_mfma_f32_16x16x32_bf16 v[58:61], v[90:93], v[166:169], v[58:61]
	v_mfma_f32_16x16x32_bf16 v[46:49], v[78:81], v[196:199], v[46:49]
	v_mfma_f32_16x16x32_bf16 v[42:45], v[90:93], v[196:199], v[42:45]
	v_mfma_f32_16x16x32_bf16 v[30:33], v[78:81], v[204:207], v[30:33]
	v_mfma_f32_16x16x32_bf16 v[26:29], v[90:93], v[204:207], v[26:29]
	v_mfma_f32_16x16x32_bf16 v[14:17], v[78:81], v[212:215], v[14:17]
	v_mfma_f32_16x16x32_bf16 v[10:13], v[90:93], v[212:215], v[10:13]
	s_setprio 0
	s_setprio 1
	v_mfma_f32_16x16x32_bf16 v[54:57], v[94:97], v[162:165], v[54:57]
	v_mfma_f32_16x16x32_bf16 v[50:53], v[102:105], v[162:165], v[50:53]
	v_mfma_f32_16x16x32_bf16 v[38:41], v[94:97], v[192:195], v[38:41]
	v_mfma_f32_16x16x32_bf16 v[34:37], v[102:105], v[192:195], v[34:37]
	v_mfma_f32_16x16x32_bf16 v[22:25], v[94:97], v[200:203], v[22:25]
	v_mfma_f32_16x16x32_bf16 v[18:21], v[102:105], v[200:203], v[18:21]
	v_mfma_f32_16x16x32_bf16 v[6:9], v[94:97], v[208:211], v[6:9]
	v_mfma_f32_16x16x32_bf16 v[2:5], v[102:105], v[208:211], v[2:5]
	v_mfma_f32_16x16x32_bf16 v[54:57], v[98:101], v[166:169], v[54:57]
	v_mfma_f32_16x16x32_bf16 v[50:53], v[110:113], v[166:169], v[50:53]
	v_mfma_f32_16x16x32_bf16 v[38:41], v[98:101], v[196:199], v[38:41]
	v_mfma_f32_16x16x32_bf16 v[34:37], v[110:113], v[196:199], v[34:37]
	v_mfma_f32_16x16x32_bf16 v[22:25], v[98:101], v[204:207], v[22:25]
	v_mfma_f32_16x16x32_bf16 v[18:21], v[110:113], v[204:207], v[18:21]
	v_mfma_f32_16x16x32_bf16 v[6:9], v[98:101], v[212:215], v[6:9]
	v_mfma_f32_16x16x32_bf16 v[2:5], v[110:113], v[212:215], v[2:5]
	s_setprio 0
	s_add_i32 s49, s49, 2
	s_add_u32 s22, s22, 0x100
	s_addc_u32 s23, s23, 0
	s_add_u32 s45, s45, 0x100
	s_addc_u32 s47, s47, 0
	s_barrier
	s_cmp_gt_u32 s49, 13
	s_cbranch_scc0 .LBB0_157
